# forgetting-mixer tile loop: staging waits vmcnt(3,2) instead of (1,0) when the step issued its own loads, drain at loop exit (on top of v_all2)
# speedup vs baseline: 1.0059x; 1.0059x over previous
.LBB0_354:
	v_mov_b32_e32 v0, s23
	ds_read_b32 v122, v0
	s_waitcnt lgkmcnt(0)
	v_pk_add_f32 v[34:35], v[198:199], v[122:123]
	s_nop 0
	v_cmp_gt_f32_e32 vcc, v34, v35
	s_cmp_lg_u64 vcc, 0
	s_cselect_b64 s[14:15], -1, 0
	s_and_saveexec_b64 s[16:17], s[40:41]
	v_cndmask_b32_e64 v0, 0, 1, s[14:15]
	v_mov_b32_e32 v34, s29
	ds_write_b32 v34, v0
	s_or_b64 exec, exec, s[16:17]
	s_add_i32 s72, s68, -1
	s_cmp_lt_u32 s72, s85
	s_cselect_b64 s[18:19], -1, 0
	s_cmp_ge_u32 s72, s85
	s_cbranch_scc1 .LBB0_359
	v_add_u32_e32 v0, 0xaa00, v135
	s_and_b64 vcc, exec, s[36:37]
	s_cmp_lg_u64 s[10:11], 0
	s_cbranch_scc1 .Lfv_a_own
	s_waitcnt vmcnt(1)
	ds_write_b128 v134, v[90:93] offset:9216
	s_waitcnt vmcnt(0)
	s_branch .Lfv_a_join
.Lfv_a_own:
	s_waitcnt vmcnt(3)
	ds_write_b128 v134, v[90:93] offset:9216
	s_waitcnt vmcnt(2)
.Lfv_a_join:
	ds_write2_b64 v0, v[94:95], v[96:97] offset1:1
	s_cbranch_vccnz .LBB0_359
	v_mov_b32_e32 v0, v141
	v_mbcnt_lo_u32_b32 v36, -1, 0
	v_mbcnt_hi_u32_b32 v36, -1, v36
	v_add_f32_dpp v0, v0, v0 row_shl:1 row_mask:0xf bank_mask:0xf bound_ctrl:0
	s_nop 1
	v_add_f32_dpp v0, v0, v0 row_shl:2 row_mask:0xf bank_mask:0xf bound_ctrl:0
	s_nop 1
	v_add_f32_dpp v0, v0, v0 row_shl:4 row_mask:0xf bank_mask:0xf bound_ctrl:0
	s_nop 1
	v_add_f32_dpp v0, v0, v0 row_shl:8 row_mask:0xf bank_mask:0xf bound_ctrl:0
	v_cmp_gt_u32_e32 vcc, 16, v36
	s_nop 0
	v_readlane_b32 s99, v0, 48
	v_readlane_b32 s100, v0, 32
	v_readlane_b32 s101, v0, 16
	v_mov_b32_e32 v34, 0
	s_nop 0
	v_mov_b32_e32 v35, s99
	v_cndmask_b32_e64 v34, v34, v35, s[50:51]
	v_add_f32_e32 v35, s100, v34
	v_cndmask_b32_e64 v34, v34, v35, s[38:39]
	v_add_f32_e32 v35, s101, v34
	v_cndmask_b32_e32 v34, v34, v35, vcc
	v_add_f32_e32 v0, v0, v34
	s_nop 0
	v_readlane_b32 s99, v0, 0
	v_add_f32_e32 v0, v137, v0
	v_sub_f32_e32 v0, v0, v141
	v_mul_f32_e32 v0, 0x3fb8aa3b, v0
	ds_write_b32 v147, v0 offset:256
	v_add_f32_e32 v137, s99, v137

.LBB0_380:
	v_mov_b32_e32 v0, s60
	ds_read_b32 v120, v0
	s_waitcnt lgkmcnt(0)
	v_pk_add_f32 v[34:35], v[198:199], v[120:121]
	s_nop 0
	v_cmp_gt_f32_e32 vcc, v34, v35
	s_cmp_lg_u64 vcc, 0
	s_cselect_b64 s[14:15], -1, 0
	s_and_saveexec_b64 s[16:17], s[40:41]
	v_cndmask_b32_e64 v0, 0, 1, s[14:15]
	v_mov_b32_e32 v34, s29
	ds_write_b32 v34, v0 offset:32
	s_or_b64 exec, exec, s[16:17]
	s_andn2_b64 vcc, exec, s[10:11]
	s_cbranch_vccnz .LBB0_385
	s_and_b64 vcc, exec, s[36:37]
	s_cmp_lt_u32 s72, s85
	s_cbranch_scc1 .Lfv_b_own
	s_waitcnt vmcnt(1)
	ds_write_b128 v134, v[82:85]
	s_waitcnt vmcnt(0)
	s_branch .Lfv_b_join
.Lfv_b_own:
	s_waitcnt vmcnt(3)
	ds_write_b128 v134, v[82:85]
	s_waitcnt vmcnt(2)
.Lfv_b_join:
	ds_write2_b64 v136, v[86:87], v[88:89] offset1:1
	s_cbranch_vccnz .LBB0_385
	v_mov_b32_e32 v0, v133
	v_mbcnt_lo_u32_b32 v36, -1, 0
	v_mbcnt_hi_u32_b32 v36, -1, v36
	v_add_f32_dpp v0, v0, v0 row_shl:1 row_mask:0xf bank_mask:0xf bound_ctrl:0
	s_nop 1
	v_add_f32_dpp v0, v0, v0 row_shl:2 row_mask:0xf bank_mask:0xf bound_ctrl:0
	s_nop 1
	v_add_f32_dpp v0, v0, v0 row_shl:4 row_mask:0xf bank_mask:0xf bound_ctrl:0
	s_nop 1
	v_add_f32_dpp v0, v0, v0 row_shl:8 row_mask:0xf bank_mask:0xf bound_ctrl:0
	v_cmp_gt_u32_e32 vcc, 16, v36
	s_nop 0
	v_readlane_b32 s99, v0, 48
	v_readlane_b32 s100, v0, 32
	v_readlane_b32 s101, v0, 16
	v_mov_b32_e32 v34, 0
	s_nop 0
	v_mov_b32_e32 v35, s99
	v_cndmask_b32_e64 v34, v34, v35, s[50:51]
	v_add_f32_e32 v35, s100, v34
	v_cndmask_b32_e64 v34, v34, v35, s[38:39]
	v_add_f32_e32 v35, s101, v34
	v_cndmask_b32_e32 v34, v34, v35, vcc
	v_add_f32_e32 v0, v0, v34
	s_nop 0
	v_readlane_b32 s99, v0, 0
	v_add_f32_e32 v0, v137, v0
	v_sub_f32_e32 v0, v0, v133
	v_mul_f32_e32 v0, 0x3fb8aa3b, v0
	ds_write_b32 v147, v0
	v_add_f32_e32 v137, s99, v137

; __device__ __forceinline__ float xhalf_sum(float v) { auto rr = __builtin_amdgcn_permlane32_swap(__float_as_uint(v), __float_as_uint(v), false, false); return __uint_as_float(rr[0]) + __uint_as_float(rr[1]); }
; template <int MODE> ...
;     ...
;     const float lt = xhalf_sum(lsum);
;     if (hi == 0) wsf[r32] = 1.0f / lt;
;     asm volatile("s_waitcnt lgkmcnt(0)" ::: "memory");
.LBB0_386:
	s_waitcnt vmcnt(0)
	v_mov_b32_e32 v0, v151
	s_nop 1
	v_permlane32_swap_b32_e32 v151, v0
	s_and_saveexec_b64 s[6:7], s[38:39]
	s_cbranch_execz .LBB0_388
	v_add_f32_e32 v0, v151, v0
	v_div_scale_f32 v34, s[8:9], v0, v0, 1.0
	v_rcp_f32_e32 v35, v34
	v_div_scale_f32 v36, vcc, 1.0, v0, 1.0
	v_fma_f32 v37, -v34, v35, 1.0
	v_fmac_f32_e32 v35, v37, v35
	v_mul_f32_e32 v37, v36, v35
	v_fma_f32 v38, -v34, v37, v36
	v_fmac_f32_e32 v37, v38, v35
	v_fma_f32 v34, -v34, v37, v36
	v_div_fmas_f32 v34, v34, v35, v37
	v_div_fixup_f32 v0, v34, v0, 1.0
	ds_write_b32 v140, v0
